# LN1 and LN2 row loops: dropped hipcc's conservative s_waitcnt vmcnt that drained the just-issued next-row prefetch (LN2) or the previous row's store acks (LN1) before each row; prologue loads drained
# speedup vs baseline: 1.0048x; 1.0017x over previous
.LBB0_1393:
	s_sub_i32 s8, s24, s3
	s_add_i32 s8, s8, 15
	s_ashr_i32 s25, s8, 4
	s_cmp_lt_i32 s25, 1
	s_cbranch_scc1 .LBB0_1415
	v_and_b32_e32 v20, 64, v19
	v_add_u32_e32 v20, 64, v20
	v_xor_b32_e32 v21, 1, v19
	v_cmp_lt_i32_e32 vcc, v21, v20
	s_and_b32 s8, s90, 0xffffffc0
	s_add_u32 s26, s14, 0x6fc18000
	v_cndmask_b32_e32 v21, v19, v21, vcc
	v_lshlrev_b32_e32 v156, 2, v21
	v_xor_b32_e32 v21, 2, v19
	v_cmp_lt_i32_e32 vcc, v21, v20
	s_addc_u32 s27, s15, 0
	s_lshl_b32 s9, s12, 2
	v_cndmask_b32_e32 v21, v19, v21, vcc
	v_lshlrev_b32_e32 v157, 2, v21
	v_xor_b32_e32 v21, 4, v19
	v_cmp_lt_i32_e32 vcc, v21, v20
	v_ashrrev_i32_e32 v39, 31, v38
	s_add_i32 s12, s9, 0
	v_cndmask_b32_e32 v21, v19, v21, vcc
	v_lshlrev_b32_e32 v158, 2, v21
	v_xor_b32_e32 v21, 8, v19
	v_cmp_lt_i32_e32 vcc, v21, v20
	s_add_i32 s16, 0, 0x20100
	v_lshl_add_u64 v[40:41], v[38:39], 1, s[6:7]
	v_cndmask_b32_e32 v21, v19, v21, vcc
	v_lshlrev_b32_e32 v159, 2, v21
	v_xor_b32_e32 v21, 16, v19
	v_cmp_lt_i32_e32 vcc, v21, v20
	v_cmp_eq_u32_e64 s[6:7], 0, v16
	s_add_i32 s9, s16, s9
	v_cndmask_b32_e32 v21, v19, v21, vcc
	v_lshlrev_b32_e32 v160, 2, v21
	v_xor_b32_e32 v21, 32, v19
	v_cmp_lt_i32_e32 vcc, v21, v20
	v_lshlrev_b32_e32 v20, 5, v16
	v_mov_b32_e32 v37, 0
	v_cndmask_b32_e32 v19, v19, v21, vcc
	v_lshlrev_b32_e32 v161, 2, v19
	v_add_u32_e32 v19, s8, v16
	v_mul_u32_u24_e32 v16, 0x2010, v17
	v_lshlrev_b32_e32 v21, 2, v18
	v_add3_u32 v163, s12, v16, v21
	v_lshlrev_b32_e32 v16, 8, v18
	s_movk_i32 s8, 0x100
	v_add3_u32 v164, s9, v16, v36
	v_cmp_gt_i32_e64 s[8:9], s8, v19
	v_ashrrev_i32_e32 v165, 4, v19
	v_lshl_add_u32 v166, v19, 2, s16
	v_lshl_add_u64 v[18:19], s[14:15], 0, v[36:37]
	s_mov_b64 s[16:17], 0x5c1d8000
	s_mul_i32 s28, s33, 0x2010
	v_lshl_add_u64 v[42:43], v[18:19], 0, s[16:17]
	s_mov_b32 s12, 0xc000
	v_mov_b64_e32 v[18:19], s[14:15]
	s_add_i32 s18, s28, 0
	v_mad_u64_u32 v[16:17], s[16:17], v17, s12, v[18:19]
	s_add_i32 s29, s28, 0x10080
	s_add_i32 s19, s18, 0x10080
	s_mov_b64 s[16:17], 0x6e358000
	s_add_u32 s30, s14, 0x6ff90000
	v_lshl_add_u64 v[44:45], v[16:17], 0, s[16:17]
	v_add_u32_e32 v16, 0x404, v38
	v_add_u32_e32 v18, 0x604, v38
	s_addc_u32 s31, s15, 0
	v_add_u32_e32 v162, 0, v20
	v_add_u32_e32 v46, 0x204, v38
	v_ashrrev_i32_e32 v17, 31, v16
	v_ashrrev_i32_e32 v19, 31, v18
	v_add_u32_e32 v167, s18, v20
	v_add_u32_e32 v168, s19, v20
	v_lshl_add_u64 v[20:21], s[14:15], 0, v[38:39]
	s_mov_b64 s[14:15], 0x6e418000
	s_mov_b32 s13, 0
	v_ashrrev_i32_e32 v47, 31, v46
	v_lshl_add_u64 v[48:49], v[20:21], 0, s[14:15]
	s_movk_i32 s34, 0x1000
	v_mov_b32_e32 v169, 0x3727c5ac
	s_mov_b32 s35, 0x800000
	s_mov_b32 s36, 0x3fb8aa3b
	s_mov_b32 s37, 0xc2ce8ed0
	s_mov_b32 s38, 0x42b17218
	v_lshlrev_b64 v[50:51], 2, v[16:17]
	v_lshlrev_b64 v[52:53], 2, v[18:19]
	v_mov_b32_e32 v170, 0x7f800000
	s_mov_b32 s39, s33
	s_waitcnt vmcnt(0)
	s_branch .LBB0_1396

.LBB0_1396:
	s_add_i32 s18, s3, s39
	s_add_i32 s16, s18, 8
	s_cmp_ge_i32 s16, s24
	s_cselect_b64 s[20:21], -1, 0
	v_mov_b64_e32 v[30:31], v[14:15]
	v_mov_b64_e32 v[18:19], v[2:3]
	v_mov_b64_e32 v[22:23], v[6:7]
	v_mov_b64_e32 v[26:27], v[10:11]
	s_and_b64 vcc, exec, s[20:21]
	v_mov_b64_e32 v[28:29], v[12:13]
	v_mov_b64_e32 v[16:17], v[0:1]
	v_mov_b64_e32 v[20:21], v[4:5]
	v_mov_b64_e32 v[24:25], v[8:9]
	s_cbranch_vccnz .LBB0_1399
	s_ashr_i32 s17, s16, 31
	s_lshl_b64 s[14:15], s[16:17], 12
	v_lshl_add_u64 v[28:29], v[40:41], 0, s[14:15]
	global_load_dwordx4 v[24:27], v[28:29], off
	global_load_dwordx4 v[20:23], v[28:29], off offset:1024
	global_load_dwordx4 v[16:19], v[28:29], off offset:2048
	s_nop 0
	global_load_dwordx4 v[28:31], v[28:29], off offset:3072
	s_cmp_ge_i32 s18, s24
	s_mov_b64 s[14:15], -1
	s_cbranch_scc1 .LBB0_1400

.LBB0_1404:
	s_add_i32 s14, s18, 16
	v_mov_b64_e32 v[12:13], v[28:29]
	v_mov_b64_e32 v[0:1], v[16:17]
	v_mov_b64_e32 v[4:5], v[20:21]
	v_mov_b64_e32 v[8:9], v[24:25]
	s_cmp_ge_i32 s14, s24
	v_mov_b64_e32 v[14:15], v[30:31]
	v_mov_b64_e32 v[2:3], v[18:19]
	v_mov_b64_e32 v[6:7], v[22:23]
	v_mov_b64_e32 v[10:11], v[26:27]
	s_cbranch_scc1 .LBB0_1407
	s_ashr_i32 s15, s14, 31
	s_lshl_b64 s[14:15], s[14:15], 12
	v_lshl_add_u64 v[12:13], v[40:41], 0, s[14:15]
	global_load_dwordx4 v[8:11], v[12:13], off
	global_load_dwordx4 v[4:7], v[12:13], off offset:1024
	global_load_dwordx4 v[0:3], v[12:13], off offset:2048
	s_nop 0
	global_load_dwordx4 v[12:15], v[12:13], off offset:3072
	s_andn2_b64 vcc, exec, s[20:21]
	s_mov_b64 s[14:15], -1
	s_cbranch_vccz .LBB0_1408

.LBB0_1837:
	s_or_b64 exec, exec, s[18:19]
	s_add_u32 s27, s16, 0x6fc18000
	s_addc_u32 s28, s17, 0
	s_lshl_b64 s[18:19], s[22:23], 3
	s_add_u32 s18, s27, s18
	s_addc_u32 s19, s28, s19
	global_load_dwordx2 v[44:45], v33, s[18:19]
	v_and_b32_e32 v80, 64, v4
	v_add_u32_e32 v0, 64, v80
	v_xor_b32_e32 v1, 1, v4
	v_cmp_lt_i32_e32 vcc, v1, v0
	v_lshl_add_u64 v[2:3], s[16:17], 0, v[32:33]
	s_mov_b64 s[18:19], 0x333d8000
	v_cndmask_b32_e32 v1, v4, v1, vcc
	v_lshlrev_b32_e32 v81, 2, v1
	v_xor_b32_e32 v1, 2, v4
	v_cmp_lt_i32_e32 vcc, v1, v0
	v_lshl_add_u32 v87, v32, 2, 0
	v_mov_b32_e32 v88, 0x3727c5ac
	v_cndmask_b32_e32 v1, v4, v1, vcc
	v_lshlrev_b32_e32 v82, 2, v1
	v_xor_b32_e32 v1, 4, v4
	v_cmp_lt_i32_e32 vcc, v1, v0
	v_mov_b32_e32 v89, v33
	s_nop 0
	v_cndmask_b32_e32 v1, v4, v1, vcc
	v_lshlrev_b32_e32 v83, 2, v1
	v_xor_b32_e32 v1, 8, v4
	v_cmp_lt_i32_e32 vcc, v1, v0
	s_nop 1
	v_cndmask_b32_e32 v1, v4, v1, vcc
	v_lshlrev_b32_e32 v84, 2, v1
	v_xor_b32_e32 v1, 16, v4
	v_cmp_lt_i32_e32 vcc, v1, v0
	s_nop 1
	v_cndmask_b32_e32 v1, v4, v1, vcc
	v_lshlrev_b32_e32 v85, 2, v1
	v_xor_b32_e32 v1, 32, v4
	v_cmp_lt_i32_e32 vcc, v1, v0
	s_nop 1
	v_cndmask_b32_e32 v0, v4, v1, vcc
	v_lshlrev_b32_e32 v86, 2, v0
	v_lshlrev_b32_e32 v0, 1, v32
	v_mov_b32_e32 v1, v33
	v_lshl_add_u64 v[34:35], s[14:15], 0, v[0:1]
	s_mov_b64 s[14:15], 0x68358000
	v_lshl_add_u64 v[36:37], v[2:3], 0, s[14:15]
	s_mov_b32 s15, 0
	v_lshl_add_u64 v[0:1], s[16:17], 0, v[0:1]
	s_mov_b64 s[16:17], 0x561d8000
	v_lshl_add_u64 v[38:39], v[0:1], 0, s[16:17]
	s_mov_b32 s17, 1.0
	s_mov_b32 s16, s15
	v_lshl_add_u64 v[40:41], v[0:1], 0, s[18:19]
	v_mov_b64_e32 v[42:43], s[16:17]
	s_mov_b32 s16, 0x3fb504f3
	s_mov_b32 s17, 0x800000
	s_waitcnt vmcnt(0)
	s_branch .LBB0_1840

.LBB0_1844:
	v_cmp_lt_i32_e32 vcc, -1, v90
	s_and_b32 s14, vcc_lo, 0xffff
	s_cmp_eq_u64 s[14:15], 0
	s_cbranch_scc1 .LBB0_1838
	v_mov_b32_e32 v76, 0
	s_mov_b64 s[24:25], s[14:15]
	v_mov_b32_e32 v77, v76
	v_mov_b32_e32 v74, v76
	v_mov_b32_e32 v75, v76
	v_mov_b32_e32 v70, v76
	v_mov_b32_e32 v71, v76
	v_mov_b32_e32 v72, v76
	v_mov_b32_e32 v73, v76
	v_mov_b32_e32 v68, v76
	v_mov_b32_e32 v69, v76
	v_mov_b32_e32 v66, v76
	v_mov_b32_e32 v67, v76
	v_mov_b32_e32 v62, v76
	v_mov_b32_e32 v63, v76
	v_mov_b32_e32 v64, v76
	v_mov_b32_e32 v65, v76
	v_mov_b32_e32 v58, v76
	v_mov_b32_e32 v59, v76
	v_mov_b32_e32 v60, v76
	v_mov_b32_e32 v61, v76
	v_mov_b32_e32 v56, v76
	v_mov_b32_e32 v57, v76
	v_mov_b32_e32 v54, v76
	v_mov_b32_e32 v55, v76
	v_mov_b32_e32 v50, v76
	v_mov_b32_e32 v51, v76
	v_mov_b32_e32 v52, v76
	v_mov_b32_e32 v53, v76
	v_mov_b32_e32 v46, v76
	v_mov_b32_e32 v47, v76
	v_mov_b32_e32 v48, v76
	v_mov_b32_e32 v49, v76
	s_branch .LBB0_1847

.LBB0_1847:
	s_add_u32 s30, s24, -1
	s_addc_u32 s31, s25, -1
	s_ff1_i32_b64 s14, s[24:25]
	s_and_b64 s[24:25], s[30:31], s[24:25]
	s_cmp_eq_u64 s[24:25], 0
	s_cselect_b64 s[30:31], -1, 0
	s_ff1_i32_b64 s19, s[24:25]
	s_and_b64 vcc, s[30:31], exec
	s_cselect_b32 s19, s14, s19
	v_or_b32_e32 v32, s14, v80
	v_or_b32_e32 v92, s19, v80
	v_lshlrev_b32_e32 v32, 2, v32
	v_lshlrev_b32_e32 v95, 2, v92
	ds_bpermute_b32 v94, v32, v90
	ds_bpermute_b32 v93, v95, v90
	ds_bpermute_b32 v92, v32, v91
	v_mov_b32_e32 v32, 0
	s_cbranch_vccnz .LBB0_1846
	ds_bpermute_b32 v32, v95, v91
	s_waitcnt lgkmcnt(0)
	v_mul_f32_e32 v32, 0x3e000000, v32
	s_branch .LBB0_1846

.LBB0_3050:
	s_or_b64 exec, exec, s[14:15]
	s_add_u32 s20, s6, 0x6fc18000
	s_addc_u32 s21, s7, 0
	s_lshl_b64 s[14:15], s[10:11], 3
	s_add_u32 s14, s20, s14
	s_addc_u32 s15, s21, s15
	global_load_dwordx2 v[50:51], v33, s[14:15]
	v_and_b32_e32 v86, 64, v4
	v_add_u32_e32 v0, 64, v86
	v_xor_b32_e32 v1, 1, v4
	v_cmp_lt_i32_e32 vcc, v1, v0
	v_mov_b32_e32 v94, 0x3727c5ac
	v_mov_b32_e32 v95, v33
	v_cndmask_b32_e32 v1, v4, v1, vcc
	v_lshlrev_b32_e32 v87, 2, v1
	v_xor_b32_e32 v1, 2, v4
	v_cmp_lt_i32_e32 vcc, v1, v0
	s_nop 1
	v_cndmask_b32_e32 v1, v4, v1, vcc
	v_lshlrev_b32_e32 v88, 2, v1
	v_xor_b32_e32 v1, 4, v4
	v_cmp_lt_i32_e32 vcc, v1, v0
	s_nop 1
	v_cndmask_b32_e32 v1, v4, v1, vcc
	v_lshlrev_b32_e32 v89, 2, v1
	v_xor_b32_e32 v1, 8, v4
	v_cmp_lt_i32_e32 vcc, v1, v0
	s_nop 1
	v_cndmask_b32_e32 v1, v4, v1, vcc
	v_lshlrev_b32_e32 v90, 2, v1
	v_xor_b32_e32 v1, 16, v4
	v_cmp_lt_i32_e32 vcc, v1, v0
	s_nop 1
	v_cndmask_b32_e32 v1, v4, v1, vcc
	v_lshlrev_b32_e32 v91, 2, v1
	v_xor_b32_e32 v1, 32, v4
	v_cmp_lt_i32_e32 vcc, v1, v0
	s_nop 1
	v_cndmask_b32_e32 v0, v4, v1, vcc
	v_lshlrev_b32_e32 v92, 2, v0
	v_lshlrev_b32_e32 v0, 1, v32
	v_mov_b32_e32 v1, v33
	v_lshl_add_u64 v[34:35], s[12:13], 0, v[0:1]
	v_lshl_add_u64 v[0:1], s[6:7], 0, v[32:33]
	s_mov_b64 s[6:7], 0x68358000
	v_lshlrev_b32_e32 v32, 2, v32
	v_lshl_add_u64 v[36:37], v[0:1], 0, s[6:7]
	v_or_b32_e32 v0, 0x1000, v32
	v_mov_b32_e32 v1, v33
	v_lshl_add_u64 v[40:41], s[4:5], 0, v[0:1]
	v_or_b32_e32 v0, 0x1010, v32
	s_mov_b32 s7, 0
	v_add_u32_e32 v93, 0, v32
	v_lshl_add_u64 v[38:39], s[4:5], 0, v[32:33]
	v_lshl_add_u64 v[42:43], s[4:5], 0, v[0:1]
	v_or_b32_e32 v0, 0x1800, v32
	v_or_b32_e32 v32, 0x1810, v32
	v_lshl_add_u64 v[44:45], s[4:5], 0, v[0:1]
	v_lshl_add_u64 v[46:47], s[4:5], 0, v[32:33]
	s_mov_b32 s5, 1.0
	s_mov_b32 s4, s7
	v_mov_b64_e32 v[48:49], s[4:5]
	s_mov_b32 s4, 0x3fb504f3
	s_mov_b32 s5, 0x800000
	s_waitcnt vmcnt(0)
	s_branch .LBB0_3053

.LBB0_3057:
	v_cmp_lt_i32_e32 vcc, -1, v96
	s_and_b32 s6, vcc_lo, 0xffff
	s_cmp_eq_u64 s[6:7], 0
	s_cbranch_scc1 .LBB0_3051
	v_mov_b32_e32 v80, 0
	s_mov_b64 s[16:17], s[6:7]
	v_mov_b32_e32 v81, v80
	v_mov_b32_e32 v82, v80
	v_mov_b32_e32 v83, v80
	v_mov_b32_e32 v76, v80
	v_mov_b32_e32 v77, v80
	v_mov_b32_e32 v78, v80
	v_mov_b32_e32 v79, v80
	v_mov_b32_e32 v74, v80
	v_mov_b32_e32 v75, v80
	v_mov_b32_e32 v72, v80
	v_mov_b32_e32 v73, v80
	v_mov_b32_e32 v68, v80
	v_mov_b32_e32 v69, v80
	v_mov_b32_e32 v70, v80
	v_mov_b32_e32 v71, v80
	v_mov_b32_e32 v64, v80
	v_mov_b32_e32 v65, v80
	v_mov_b32_e32 v66, v80
	v_mov_b32_e32 v67, v80
	v_mov_b32_e32 v62, v80
	v_mov_b32_e32 v63, v80
	v_mov_b32_e32 v60, v80
	v_mov_b32_e32 v61, v80
	v_mov_b32_e32 v56, v80
	v_mov_b32_e32 v57, v80
	v_mov_b32_e32 v58, v80
	v_mov_b32_e32 v59, v80
	v_mov_b32_e32 v52, v80
	v_mov_b32_e32 v53, v80
	v_mov_b32_e32 v54, v80
	v_mov_b32_e32 v55, v80
	s_branch .LBB0_3060

.LBB0_3060:
	s_add_u32 s22, s16, -1
	s_addc_u32 s23, s17, -1
	s_ff1_i32_b64 s6, s[16:17]
	s_and_b64 s[16:17], s[22:23], s[16:17]
	s_cmp_eq_u64 s[16:17], 0
	s_cselect_b64 s[22:23], -1, 0
	s_ff1_i32_b64 s11, s[16:17]
	s_and_b64 vcc, s[22:23], exec
	s_cselect_b32 s11, s6, s11
	v_or_b32_e32 v32, s6, v86
	v_or_b32_e32 v98, s11, v86
	v_lshlrev_b32_e32 v32, 2, v32
	v_lshlrev_b32_e32 v101, 2, v98
	ds_bpermute_b32 v100, v32, v96
	ds_bpermute_b32 v99, v101, v96
	ds_bpermute_b32 v98, v32, v97
	v_mov_b32_e32 v32, 0
	s_cbranch_vccnz .LBB0_3059
	ds_bpermute_b32 v32, v101, v97
	s_waitcnt lgkmcnt(0)
	v_mul_f32_e32 v32, 0x3e000000, v32
	s_branch .LBB0_3059
